# grid barrier regrouped: 8 arrival words + 8 release flags + top counter (blockIdx&7 groups) instead of 512 atomics and 512 pollers on one word; same release/acquire fences
# speedup vs baseline: 1.3263x; 1.0800x over previous
.LBB0_91:
	s_add_u32 s92, s30, 0x1e561000
	s_addc_u32 s93, s31, 0
	v_readlane_b32 s6, v251, 3
	s_waitcnt lgkmcnt(0)
	s_cmp_gt_i32 s53, 1
	v_readlane_b32 s7, v251, 4
	s_cselect_b64 s[4:5], -1, 0
	s_and_b64 s[2:3], s[2:3], s[6:7]
	s_and_b64 s[2:3], s[2:3], s[4:5]
	s_andn2_b64 vcc, exec, s[2:3]
	s_cbranch_vccnz .LBB0_99
	s_waitcnt vmcnt(0) lgkmcnt(0)
	v_and_b32_e32 v1, 0x3ff, v0
	v_cmp_eq_u32_e32 vcc, 0, v1
	s_barrier
	s_and_saveexec_b64 s[2:3], vcc
	s_cbranch_execz .LBB0_98
	s_mov_b64 s[6:7], exec
	buffer_wbl2 sc1
	s_waitcnt vmcnt(0)
	s_waitcnt vmcnt(0)
	s_sub_i32 s98, 1, s52
	v_readlane_b32 s99, v251, 0
	s_and_b32 s99, s99, 7
	s_add_u32 s100, s59, 7
	s_sub_u32 s100, s100, s99
	s_lshr_b32 s100, s100, 3
	s_mul_i32 s100, s100, s98
	s_lshl_b32 s99, s99, 6
	v_mov_b32_e32 v252, s99
	v_mov_b32_e32 v253, 1
	v_mov_b32_e32 v255, 0
	global_atomic_add v254, v252, v253, s[92:93] offset:256 sc0
	s_waitcnt vmcnt(0)
	v_add_u32_e32 v254, 1, v254
	v_cmp_eq_u32_e32 vcc, s100, v254
	s_cbranch_vccz .Lgb_wait_0
	global_atomic_add v255, v253, s[92:93]
	s_min_u32 s101, s59, 8
	s_mul_i32 s101, s101, s98
.Lgb_top_0:
	global_load_dword v254, v255, s[92:93] sc1
	s_waitcnt vmcnt(0)
	v_cmp_gt_u32_e32 vcc, s101, v254
	s_cbranch_vccz .Lgb_pub_0
	s_sleep 1
	s_branch .Lgb_top_0
.Lgb_pub_0:
	v_mov_b32_e32 v254, s98
	global_store_dword v252, v254, s[92:93] offset:1024 sc0 sc1
	s_waitcnt vmcnt(0)
	s_branch .Lgb_done_0
.Lgb_wait_0:
	global_load_dword v254, v252, s[92:93] offset:1024 sc1
	s_waitcnt vmcnt(0)
	v_cmp_gt_u32_e32 vcc, s98, v254
	s_cbranch_vccz .Lgb_done_0
	s_sleep 4
	s_branch .Lgb_wait_0
.Lgb_done_0:
.LBB0_97:
	buffer_inv sc1
	s_waitcnt vmcnt(0)

.LBB0_104:
	v_readlane_b32 s6, v251, 3
	s_cmp_gt_i32 s53, 2
	v_readlane_b32 s7, v251, 4
	s_cselect_b64 s[4:5], -1, 0
	s_and_b64 s[2:3], s[2:3], s[6:7]
	s_and_b64 s[2:3], s[2:3], s[4:5]
	s_andn2_b64 vcc, exec, s[2:3]
	s_cbranch_vccnz .LBB0_112
	s_waitcnt vmcnt(0) lgkmcnt(0)
	v_and_b32_e32 v1, 0x3ff, v0
	v_cmp_eq_u32_e32 vcc, 0, v1
	s_barrier
	s_and_saveexec_b64 s[2:3], vcc
	s_cbranch_execz .LBB0_111
	s_mov_b64 s[6:7], exec
	buffer_wbl2 sc1
	s_waitcnt vmcnt(0)
	s_waitcnt vmcnt(0)
	s_sub_i32 s98, 2, s52
	v_readlane_b32 s99, v251, 0
	s_and_b32 s99, s99, 7
	s_add_u32 s100, s59, 7
	s_sub_u32 s100, s100, s99
	s_lshr_b32 s100, s100, 3
	s_mul_i32 s100, s100, s98
	s_lshl_b32 s99, s99, 6
	v_mov_b32_e32 v252, s99
	v_mov_b32_e32 v253, 1
	v_mov_b32_e32 v255, 0
	global_atomic_add v254, v252, v253, s[92:93] offset:256 sc0
	s_waitcnt vmcnt(0)
	v_add_u32_e32 v254, 1, v254
	v_cmp_eq_u32_e32 vcc, s100, v254
	s_cbranch_vccz .Lgb_wait_1
	global_atomic_add v255, v253, s[92:93]
	s_min_u32 s101, s59, 8
	s_mul_i32 s101, s101, s98

.LBB0_121:
.LBB0_122:
	s_waitcnt vmcnt(0) lgkmcnt(0)
	v_and_b32_e32 v182, 0x3ff, v0
	v_cmp_eq_u32_e32 vcc, 0, v182
	s_barrier
	s_and_saveexec_b64 s[2:3], vcc
	s_cbranch_execz .LBB0_128
	s_mov_b64 s[4:5], exec
	buffer_wbl2 sc1
	s_waitcnt vmcnt(0)
	s_waitcnt vmcnt(0)
	s_sub_i32 s98, 3, s52
	v_readlane_b32 s99, v251, 0
	s_and_b32 s99, s99, 7
	s_add_u32 s100, s59, 7
	s_sub_u32 s100, s100, s99
	s_lshr_b32 s100, s100, 3
	s_mul_i32 s100, s100, s98
	s_lshl_b32 s99, s99, 6
	v_mov_b32_e32 v252, s99
	v_mov_b32_e32 v253, 1
	v_mov_b32_e32 v255, 0
	global_atomic_add v254, v252, v253, s[92:93] offset:256 sc0
	s_waitcnt vmcnt(0)
	v_add_u32_e32 v254, 1, v254
	v_cmp_eq_u32_e32 vcc, s100, v254
	s_cbranch_vccz .Lgb_wait_2
	global_atomic_add v255, v253, s[92:93]
	s_min_u32 s101, s59, 8
	s_mul_i32 s101, s101, s98

.LBB0_142:
	v_readlane_b32 s0, v249, 15
	s_add_i32 s0, s0, 1
	v_readlane_b32 s4, v251, 3
	s_cmp_lt_i32 s0, s53
	v_readlane_b32 s5, v251, 4
	s_cselect_b64 s[8:9], -1, 0
	s_and_b64 s[2:3], s[4:5], s[2:3]
	s_and_b64 s[2:3], s[2:3], s[8:9]
	s_andn2_b64 vcc, exec, s[2:3]
	s_cbranch_vccnz .LBB0_150
	s_waitcnt vmcnt(0) lgkmcnt(0)
	v_readlane_b32 s4, v249, 16
	v_readlane_b32 s5, v249, 17
	s_barrier
	s_and_saveexec_b64 s[2:3], s[4:5]
	s_cbranch_execz .LBB0_149
	s_mov_b64 s[10:11], exec
	buffer_wbl2 sc1
	s_waitcnt vmcnt(0)
	s_waitcnt vmcnt(0)
	s_sub_i32 s98, s0, s52
	v_readlane_b32 s99, v251, 0
	s_and_b32 s99, s99, 7
	s_add_u32 s100, s59, 7
	s_sub_u32 s100, s100, s99
	s_lshr_b32 s100, s100, 3
	s_mul_i32 s100, s100, s98
	s_lshl_b32 s99, s99, 6
	v_mov_b32_e32 v252, s99
	v_mov_b32_e32 v253, 1
	v_mov_b32_e32 v255, 0
	global_atomic_add v254, v252, v253, s[92:93] offset:256 sc0
	s_waitcnt vmcnt(0)
	v_add_u32_e32 v254, 1, v254
	v_cmp_eq_u32_e32 vcc, s100, v254
	s_cbranch_vccz .Lgb_wait_3
	global_atomic_add v255, v253, s[92:93]
	s_min_u32 s101, s59, 8
	s_mul_i32 s101, s101, s98

.LBB0_156:
	v_readlane_b32 s2, v251, 3
	v_readlane_b32 s3, v251, 4
	s_andn2_b64 vcc, exec, s[2:3]
	s_nop 0
	v_cndmask_b32_e64 v0, 0, 1, s[2:3]
	v_cmp_ne_u32_e64 s[0:1], 1, v0
	s_nop 1
	v_writelane_b32 v249, s0, 38
	s_nop 1
	v_writelane_b32 v249, s1, 39
	s_nop 0
	v_readlane_b32 s0, v249, 15
	s_add_i32 s0, s0, 2
	s_cbranch_vccnz .LBB0_165
	s_cmp_gt_i32 s0, s52
	s_cselect_b64 s[2:3], -1, 0
	s_cmp_lt_i32 s0, s53
	s_cselect_b64 s[8:9], -1, 0
	s_and_b64 s[2:3], s[2:3], s[8:9]
	s_andn2_b64 vcc, exec, s[2:3]
	s_cbranch_vccnz .LBB0_165
	s_waitcnt vmcnt(0) lgkmcnt(0)
	v_readlane_b32 s4, v249, 16
	v_readlane_b32 s5, v249, 17
	s_barrier
	s_and_saveexec_b64 s[2:3], s[4:5]
	s_cbranch_execz .LBB0_164
	s_mov_b64 s[8:9], exec
	buffer_wbl2 sc1
	s_waitcnt vmcnt(0)
	s_waitcnt vmcnt(0)
	s_sub_i32 s98, s0, s52
	v_readlane_b32 s99, v251, 0
	s_and_b32 s99, s99, 7
	s_add_u32 s100, s59, 7
	s_sub_u32 s100, s100, s99
	s_lshr_b32 s100, s100, 3
	s_mul_i32 s100, s100, s98
	s_lshl_b32 s99, s99, 6
	v_mov_b32_e32 v252, s99
	v_mov_b32_e32 v253, 1
	v_mov_b32_e32 v255, 0
	global_atomic_add v254, v252, v253, s[92:93] offset:256 sc0
	s_waitcnt vmcnt(0)
	v_add_u32_e32 v254, 1, v254
	v_cmp_eq_u32_e32 vcc, s100, v254
	s_cbranch_vccz .Lgb_wait_4
	global_atomic_add v255, v253, s[92:93]
	s_min_u32 s101, s59, 8
	s_mul_i32 s101, s101, s98

.LBB0_179:
	v_readlane_b32 s0, v249, 38
	v_readlane_b32 s1, v249, 39
	s_and_b64 vcc, exec, s[0:1]
	v_readlane_b32 s0, v249, 15
	s_add_i32 s0, s0, 3
	s_cbranch_vccnz .LBB0_188
	s_cmp_gt_i32 s0, s52
	s_cselect_b64 s[2:3], -1, 0
	s_cmp_lt_i32 s0, s53
	s_cselect_b64 s[8:9], -1, 0
	s_and_b64 s[2:3], s[2:3], s[8:9]
	s_andn2_b64 vcc, exec, s[2:3]
	s_cbranch_vccnz .LBB0_188
	s_waitcnt vmcnt(0) lgkmcnt(0)
	v_readlane_b32 s4, v249, 16
	v_readlane_b32 s5, v249, 17
	s_barrier
	s_and_saveexec_b64 s[2:3], s[4:5]
	s_cbranch_execz .LBB0_187
	s_mov_b64 s[8:9], exec
	buffer_wbl2 sc1
	s_waitcnt vmcnt(0)
	s_waitcnt vmcnt(0)
	s_sub_i32 s98, s0, s52
	v_readlane_b32 s99, v251, 0
	s_and_b32 s99, s99, 7
	s_add_u32 s100, s59, 7
	s_sub_u32 s100, s100, s99
	s_lshr_b32 s100, s100, 3
	s_mul_i32 s100, s100, s98
	s_lshl_b32 s99, s99, 6
	v_mov_b32_e32 v252, s99
	v_mov_b32_e32 v253, 1
	v_mov_b32_e32 v255, 0
	global_atomic_add v254, v252, v253, s[92:93] offset:256 sc0
	s_waitcnt vmcnt(0)
	v_add_u32_e32 v254, 1, v254
	v_cmp_eq_u32_e32 vcc, s100, v254
	s_cbranch_vccz .Lgb_wait_5
	global_atomic_add v255, v253, s[92:93]
	s_min_u32 s101, s59, 8
	s_mul_i32 s101, s101, s98

.LBB0_205:
	v_readlane_b32 s2, v249, 38
	v_readlane_b32 s3, v249, 39
	v_readlane_b32 s0, v249, 15
	s_and_b64 vcc, exec, s[2:3]
	s_add_i32 s0, s0, 4
	s_cbranch_vccnz .LBB0_214
	s_cmp_gt_i32 s0, s52
	s_cselect_b64 s[2:3], -1, 0
	s_cmp_lt_i32 s0, s53
	s_cselect_b64 s[8:9], -1, 0
	s_and_b64 s[2:3], s[2:3], s[8:9]
	s_andn2_b64 vcc, exec, s[2:3]
	s_cbranch_vccnz .LBB0_214
	s_waitcnt vmcnt(0) lgkmcnt(0)
	v_readlane_b32 s4, v249, 16
	v_readlane_b32 s5, v249, 17
	s_barrier
	s_and_saveexec_b64 s[2:3], s[4:5]
	s_cbranch_execz .LBB0_213
	s_mov_b64 s[8:9], exec
	buffer_wbl2 sc1
	s_waitcnt vmcnt(0)
	s_waitcnt vmcnt(0)
	s_sub_i32 s98, s0, s52
	v_readlane_b32 s99, v251, 0
	s_and_b32 s99, s99, 7
	s_add_u32 s100, s59, 7
	s_sub_u32 s100, s100, s99
	s_lshr_b32 s100, s100, 3
	s_mul_i32 s100, s100, s98
	s_lshl_b32 s99, s99, 6
	v_mov_b32_e32 v252, s99
	v_mov_b32_e32 v253, 1
	v_mov_b32_e32 v255, 0
	global_atomic_add v254, v252, v253, s[92:93] offset:256 sc0
	s_waitcnt vmcnt(0)
	v_add_u32_e32 v254, 1, v254
	v_cmp_eq_u32_e32 vcc, s100, v254
	s_cbranch_vccz .Lgb_wait_6
	global_atomic_add v255, v253, s[92:93]
	s_min_u32 s101, s59, 8
	s_mul_i32 s101, s101, s98

.LBB0_257:
	v_readlane_b32 s2, v249, 38
	v_readlane_b32 s3, v249, 39
	v_readlane_b32 s0, v249, 15
	s_and_b64 vcc, exec, s[2:3]
	s_add_i32 s0, s0, 5
	s_cbranch_vccnz .LBB0_266
	s_cmp_gt_i32 s0, s52
	s_cselect_b64 s[2:3], -1, 0
	s_cmp_lt_i32 s0, s53
	s_cselect_b64 s[8:9], -1, 0
	s_and_b64 s[2:3], s[2:3], s[8:9]
	s_andn2_b64 vcc, exec, s[2:3]
	s_cbranch_vccnz .LBB0_266
	s_waitcnt vmcnt(0) lgkmcnt(0)
	v_readlane_b32 s4, v249, 16
	v_readlane_b32 s5, v249, 17
	s_waitcnt vmcnt(63) expcnt(7) lgkmcnt(15)
	s_barrier
	s_and_saveexec_b64 s[2:3], s[4:5]
	s_cbranch_execz .LBB0_265
	s_mov_b64 s[8:9], exec
	buffer_wbl2 sc1
	s_waitcnt vmcnt(0)
	s_waitcnt vmcnt(0)
	s_sub_i32 s98, s0, s52
	v_readlane_b32 s99, v251, 0
	s_and_b32 s99, s99, 7
	s_add_u32 s100, s59, 7
	s_sub_u32 s100, s100, s99
	s_lshr_b32 s100, s100, 3
	s_mul_i32 s100, s100, s98
	s_lshl_b32 s99, s99, 6
	v_mov_b32_e32 v252, s99
	v_mov_b32_e32 v253, 1
	v_mov_b32_e32 v255, 0
	global_atomic_add v254, v252, v253, s[92:93] offset:256 sc0
	s_waitcnt vmcnt(0)
	v_add_u32_e32 v254, 1, v254
	v_cmp_eq_u32_e32 vcc, s100, v254
	s_cbranch_vccz .Lgb_wait_7
	global_atomic_add v255, v253, s[92:93]
	s_min_u32 s101, s59, 8
	s_mul_i32 s101, s101, s98

.LBB0_475:
	v_readlane_b32 s2, v249, 38
	v_readlane_b32 s3, v249, 39
	v_readlane_b32 s0, v249, 15
	s_and_b64 vcc, exec, s[2:3]
	s_add_i32 s0, s0, 6
	s_cbranch_vccnz .LBB0_484
	s_cmp_gt_i32 s0, s52
	s_cselect_b64 s[2:3], -1, 0
	s_cmp_lt_i32 s0, s53
	s_cselect_b64 s[8:9], -1, 0
	s_and_b64 s[2:3], s[2:3], s[8:9]
	s_andn2_b64 vcc, exec, s[2:3]
	s_cbranch_vccnz .LBB0_484
	s_waitcnt vmcnt(0) lgkmcnt(0)
	v_readlane_b32 s4, v249, 16
	v_readlane_b32 s5, v249, 17
	s_waitcnt vmcnt(63) expcnt(7) lgkmcnt(15)
	s_barrier
	s_and_saveexec_b64 s[2:3], s[4:5]
	s_cbranch_execz .LBB0_483
	s_mov_b64 s[8:9], exec
	buffer_wbl2 sc1
	s_waitcnt vmcnt(0)
	s_waitcnt vmcnt(0)
	s_sub_i32 s98, s0, s52
	v_readlane_b32 s99, v251, 0
	s_and_b32 s99, s99, 7
	s_add_u32 s100, s59, 7
	s_sub_u32 s100, s100, s99
	s_lshr_b32 s100, s100, 3
	s_mul_i32 s100, s100, s98
	s_lshl_b32 s99, s99, 6
	v_mov_b32_e32 v252, s99
	v_mov_b32_e32 v253, 1
	v_mov_b32_e32 v255, 0
	global_atomic_add v254, v252, v253, s[92:93] offset:256 sc0
	s_waitcnt vmcnt(0)
	v_add_u32_e32 v254, 1, v254
	v_cmp_eq_u32_e32 vcc, s100, v254
	s_cbranch_vccz .Lgb_wait_8
	global_atomic_add v255, v253, s[92:93]
	s_min_u32 s101, s59, 8
	s_mul_i32 s101, s101, s98

.LBB0_588:
	v_readlane_b32 s2, v249, 38
	v_readlane_b32 s3, v249, 39
	v_readlane_b32 s0, v249, 15
	s_and_b64 vcc, exec, s[2:3]
	s_add_i32 s0, s0, 7
	s_cbranch_vccnz .LBB0_597
	s_cmp_gt_i32 s0, s52
	s_cselect_b64 s[2:3], -1, 0
	s_cmp_lt_i32 s0, s53
	s_cselect_b64 s[4:5], -1, 0
	s_and_b64 s[2:3], s[2:3], s[4:5]
	s_andn2_b64 vcc, exec, s[2:3]
	s_cbranch_vccnz .LBB0_597
	s_waitcnt vmcnt(0) lgkmcnt(0)
	s_waitcnt lgkmcnt(0)
	s_barrier
	s_mov_b64 s[2:3], exec
	v_readlane_b32 s4, v249, 16
	v_readlane_b32 s5, v249, 17
	s_and_b64 s[4:5], s[2:3], s[4:5]
	s_mov_b64 exec, s[4:5]
	s_cbranch_execz .LBB0_596
	s_mov_b64 s[8:9], exec
	buffer_wbl2 sc1
	s_waitcnt vmcnt(0)
	s_waitcnt vmcnt(0)
	s_sub_i32 s98, s0, s52
	v_readlane_b32 s99, v251, 0
	s_and_b32 s99, s99, 7
	s_add_u32 s100, s59, 7
	s_sub_u32 s100, s100, s99
	s_lshr_b32 s100, s100, 3
	s_mul_i32 s100, s100, s98
	s_lshl_b32 s99, s99, 6
	v_mov_b32_e32 v252, s99
	v_mov_b32_e32 v253, 1
	v_mov_b32_e32 v255, 0
	global_atomic_add v254, v252, v253, s[92:93] offset:256 sc0
	s_waitcnt vmcnt(0)
	v_add_u32_e32 v254, 1, v254
	v_cmp_eq_u32_e32 vcc, s100, v254
	s_cbranch_vccz .Lgb_wait_9
	global_atomic_add v255, v253, s[92:93]
	s_min_u32 s101, s59, 8
	s_mul_i32 s101, s101, s98

.LBB0_603:
	v_readlane_b32 s2, v249, 38
	v_readlane_b32 s3, v249, 39
	v_readlane_b32 s0, v249, 15
	s_and_b64 vcc, exec, s[2:3]
	s_add_i32 s0, s0, 8
	s_cbranch_vccnz .LBB0_612
	s_cmp_gt_i32 s0, s52
	s_cselect_b64 s[2:3], -1, 0
	s_cmp_lt_i32 s0, s53
	s_cselect_b64 s[4:5], -1, 0
	s_and_b64 s[2:3], s[2:3], s[4:5]
	s_andn2_b64 vcc, exec, s[2:3]
	s_cbranch_vccnz .LBB0_612
	s_waitcnt vmcnt(0) lgkmcnt(0)
	s_waitcnt lgkmcnt(0)
	s_barrier
	s_mov_b64 s[2:3], exec
	v_readlane_b32 s4, v249, 16
	v_readlane_b32 s5, v249, 17
	s_and_b64 s[4:5], s[2:3], s[4:5]
	s_mov_b64 exec, s[4:5]
	s_cbranch_execz .LBB0_611
	s_mov_b64 s[8:9], exec
	buffer_wbl2 sc1
	s_waitcnt vmcnt(0)
	s_waitcnt vmcnt(0)
	s_sub_i32 s98, s0, s52
	v_readlane_b32 s99, v251, 0
	s_and_b32 s99, s99, 7
	s_add_u32 s100, s59, 7
	s_sub_u32 s100, s100, s99
	s_lshr_b32 s100, s100, 3
	s_mul_i32 s100, s100, s98
	s_lshl_b32 s99, s99, 6
	v_mov_b32_e32 v252, s99
	v_mov_b32_e32 v253, 1
	v_mov_b32_e32 v255, 0
	global_atomic_add v254, v252, v253, s[92:93] offset:256 sc0
	s_waitcnt vmcnt(0)
	v_add_u32_e32 v254, 1, v254
	v_cmp_eq_u32_e32 vcc, s100, v254
	s_cbranch_vccz .Lgb_wait_10
	global_atomic_add v255, v253, s[92:93]
	s_min_u32 s101, s59, 8
	s_mul_i32 s101, s101, s98

.LBB0_619:
	v_readlane_b32 s2, v249, 38
	v_readlane_b32 s3, v249, 39
	v_readlane_b32 s0, v249, 15
	s_and_b64 vcc, exec, s[2:3]
	s_add_i32 s0, s0, 9
	s_cbranch_vccnz .LBB0_628
	s_cmp_gt_i32 s0, s52
	s_cselect_b64 s[2:3], -1, 0
	s_cmp_lt_i32 s0, s53
	s_cselect_b64 s[4:5], -1, 0
	s_and_b64 s[2:3], s[2:3], s[4:5]
	s_andn2_b64 vcc, exec, s[2:3]
	s_cbranch_vccnz .LBB0_628
	s_waitcnt vmcnt(0) lgkmcnt(0)
	s_waitcnt lgkmcnt(0)
	s_barrier
	s_mov_b64 s[2:3], exec
	v_readlane_b32 s4, v249, 16
	v_readlane_b32 s5, v249, 17
	s_and_b64 s[4:5], s[2:3], s[4:5]
	s_mov_b64 exec, s[4:5]
	s_cbranch_execz .LBB0_627
	s_mov_b64 s[8:9], exec
	buffer_wbl2 sc1
	s_waitcnt vmcnt(0)
	s_waitcnt vmcnt(0)
	s_sub_i32 s98, s0, s52
	v_readlane_b32 s99, v251, 0
	s_and_b32 s99, s99, 7
	s_add_u32 s100, s59, 7
	s_sub_u32 s100, s100, s99
	s_lshr_b32 s100, s100, 3
	s_mul_i32 s100, s100, s98
	s_lshl_b32 s99, s99, 6
	v_mov_b32_e32 v252, s99
	v_mov_b32_e32 v253, 1
	v_mov_b32_e32 v255, 0
	global_atomic_add v254, v252, v253, s[92:93] offset:256 sc0
	s_waitcnt vmcnt(0)
	v_add_u32_e32 v254, 1, v254
	v_cmp_eq_u32_e32 vcc, s100, v254
	s_cbranch_vccz .Lgb_wait_11
	global_atomic_add v255, v253, s[92:93]
	s_min_u32 s101, s59, 8
	s_mul_i32 s101, s101, s98

.LBB0_637:
	v_readlane_b32 s2, v249, 38
	v_readlane_b32 s3, v249, 39
	v_readlane_b32 s0, v249, 15
	s_and_b64 vcc, exec, s[2:3]
	s_add_i32 s0, s0, 10
	s_cbranch_vccnz .LBB0_646
	s_cmp_gt_i32 s0, s52
	s_cselect_b64 s[2:3], -1, 0
	s_cmp_lt_i32 s0, s53
	s_cselect_b64 s[4:5], -1, 0
	s_and_b64 s[2:3], s[2:3], s[4:5]
	s_andn2_b64 vcc, exec, s[2:3]
	s_cbranch_vccnz .LBB0_646
	s_waitcnt vmcnt(0) lgkmcnt(0)
	s_waitcnt lgkmcnt(0)
	s_barrier
	s_mov_b64 s[2:3], exec
	v_readlane_b32 s4, v249, 16
	v_readlane_b32 s5, v249, 17
	s_and_b64 s[4:5], s[2:3], s[4:5]
	s_mov_b64 exec, s[4:5]
	s_cbranch_execz .LBB0_645
	s_mov_b64 s[8:9], exec
	buffer_wbl2 sc1
	s_waitcnt vmcnt(0)
	s_waitcnt vmcnt(0)
	s_sub_i32 s98, s0, s52
	v_readlane_b32 s99, v251, 0
	s_and_b32 s99, s99, 7
	s_add_u32 s100, s59, 7
	s_sub_u32 s100, s100, s99
	s_lshr_b32 s100, s100, 3
	s_mul_i32 s100, s100, s98
	s_lshl_b32 s99, s99, 6
	v_mov_b32_e32 v252, s99
	v_mov_b32_e32 v253, 1
	v_mov_b32_e32 v255, 0
	global_atomic_add v254, v252, v253, s[92:93] offset:256 sc0
	s_waitcnt vmcnt(0)
	v_add_u32_e32 v254, 1, v254
	v_cmp_eq_u32_e32 vcc, s100, v254
	s_cbranch_vccz .Lgb_wait_12
	global_atomic_add v255, v253, s[92:93]
	s_min_u32 s101, s59, 8
	s_mul_i32 s101, s101, s98

.LBB0_652:
	v_readlane_b32 s2, v249, 38
	v_readlane_b32 s3, v249, 39
	v_readlane_b32 s0, v249, 15
	s_and_b64 vcc, exec, s[2:3]
	s_add_i32 s0, s0, 11
	s_cbranch_vccnz .LBB0_661
	s_cmp_gt_i32 s0, s52
	s_cselect_b64 s[2:3], -1, 0
	s_cmp_lt_i32 s0, s53
	s_cselect_b64 s[4:5], -1, 0
	s_and_b64 s[2:3], s[2:3], s[4:5]
	s_andn2_b64 vcc, exec, s[2:3]
	s_cbranch_vccnz .LBB0_661
	s_waitcnt vmcnt(0) lgkmcnt(0)
	s_waitcnt lgkmcnt(0)
	s_barrier
	s_mov_b64 s[2:3], exec
	v_readlane_b32 s4, v249, 16
	v_readlane_b32 s5, v249, 17
	s_and_b64 s[4:5], s[2:3], s[4:5]
	s_mov_b64 exec, s[4:5]
	s_cbranch_execz .LBB0_660
	s_mov_b64 s[8:9], exec
	buffer_wbl2 sc1
	s_waitcnt vmcnt(0)
	s_waitcnt vmcnt(0)
	s_sub_i32 s98, s0, s52
	v_readlane_b32 s99, v251, 0
	s_and_b32 s99, s99, 7
	s_add_u32 s100, s59, 7
	s_sub_u32 s100, s100, s99
	s_lshr_b32 s100, s100, 3
	s_mul_i32 s100, s100, s98
	s_lshl_b32 s99, s99, 6
	v_mov_b32_e32 v252, s99
	v_mov_b32_e32 v253, 1
	v_mov_b32_e32 v255, 0
	global_atomic_add v254, v252, v253, s[92:93] offset:256 sc0
	s_waitcnt vmcnt(0)
	v_add_u32_e32 v254, 1, v254
	v_cmp_eq_u32_e32 vcc, s100, v254
	s_cbranch_vccz .Lgb_wait_13
	global_atomic_add v255, v253, s[92:93]
	s_min_u32 s101, s59, 8
	s_mul_i32 s101, s101, s98

.LBB0_670:
	v_readlane_b32 s2, v249, 38
	v_readlane_b32 s3, v249, 39
	v_readlane_b32 s0, v249, 15
	s_and_b64 vcc, exec, s[2:3]
	s_add_i32 s0, s0, 12
	v_writelane_b32 v249, s0, 15
	s_cbranch_vccnz .Ltramp_132
	v_readlane_b32 s0, v249, 15
	s_cmp_gt_i32 s0, s52
	s_cselect_b64 s[2:3], -1, 0
	s_cmp_lt_i32 s0, s53
	s_cselect_b64 s[4:5], -1, 0
	s_and_b64 s[2:3], s[2:3], s[4:5]
	s_andn2_b64 vcc, exec, s[2:3]
	s_cbranch_vccnz .Ltramp_132
	s_waitcnt vmcnt(0) lgkmcnt(0)
	s_waitcnt lgkmcnt(0)
	s_barrier
	s_mov_b64 s[2:3], exec
	v_readlane_b32 s4, v249, 16
	v_readlane_b32 s5, v249, 17
	s_and_b64 s[4:5], s[2:3], s[4:5]
	s_mov_b64 exec, s[4:5]
	s_cbranch_execz .Ltramp_131
	s_mov_b64 s[8:9], exec
	buffer_wbl2 sc1
	s_waitcnt vmcnt(0)
	s_waitcnt vmcnt(0)
	v_readlane_b32 s98, v249, 15
	s_sub_i32 s98, s98, s52
	v_readlane_b32 s99, v251, 0
	s_and_b32 s99, s99, 7
	s_add_u32 s100, s59, 7
	s_sub_u32 s100, s100, s99
	s_lshr_b32 s100, s100, 3
	s_mul_i32 s100, s100, s98
	s_lshl_b32 s99, s99, 6
	v_mov_b32_e32 v252, s99
	v_mov_b32_e32 v253, 1
	v_mov_b32_e32 v255, 0
	global_atomic_add v254, v252, v253, s[92:93] offset:256 sc0
	s_waitcnt vmcnt(0)
	v_add_u32_e32 v254, 1, v254
	v_cmp_eq_u32_e32 vcc, s100, v254
	s_cbranch_vccz .Lgb_wait_14
	global_atomic_add v255, v253, s[92:93]
	s_min_u32 s101, s59, 8
	s_mul_i32 s101, s101, s98

.Lgb_done_14:
	s_branch .Ltramp_130
.LBB0_677:
	v_lshlrev_b32_e32 v0, 4, v10
	v_and_b32_e32 v4, 48, v0
	v_and_b32_e32 v0, -4, v10
	v_mul_u32_u24_e32 v1, 0x41, v4
	v_lshl_add_u32 v5, v1, 2, v0
	s_waitcnt lgkmcnt(0)
	s_barrier
	ds_read2_b32 v[0:1], v5 offset1:65
	ds_read2_b32 v[2:3], v5 offset0:130 offset1:195
	v_add_u32_e32 v9, 0x400, v5
	v_ashrrev_i32_e32 v6, 2, v10
	v_add_u32_e32 v13, 0x800, v5
	s_waitcnt lgkmcnt(1)
	v_max_f32_e32 v0, v0, v0
	v_med3_f32 v7, v0, s57, v194
	v_max_f32_e32 v0, v1, v1
	v_med3_f32 v8, v0, s57, v194
	s_waitcnt lgkmcnt(0)
	v_max_f32_e32 v2, v2, v2
	ds_read2_b32 v[0:1], v9 offset0:4 offset1:69
	v_med3_f32 v10, v2, s57, v194
	v_max_f32_e32 v2, v3, v3
	v_med3_f32 v11, v2, s57, v194
	ds_read2_b32 v[2:3], v9 offset0:134 offset1:199
	s_waitcnt lgkmcnt(1)
	v_max_f32_e32 v0, v0, v0
	v_med3_f32 v9, v0, s57, v194
	v_max_f32_e32 v0, v1, v1
	v_med3_f32 v12, v0, s57, v194
	s_waitcnt lgkmcnt(0)
	v_max_f32_e32 v2, v2, v2
	ds_read2_b32 v[0:1], v13 offset0:8 offset1:73
	v_med3_f32 v14, v2, s57, v194
	v_max_f32_e32 v2, v3, v3
	v_med3_f32 v15, v2, s57, v194
	ds_read2_b32 v[2:3], v13 offset0:138 offset1:203
	s_waitcnt lgkmcnt(1)
	v_max_f32_e32 v0, v0, v0
	v_med3_f32 v13, v0, s57, v194
	v_max_f32_e32 v0, v1, v1
	v_add_u32_e32 v5, 0xc00, v5
	v_med3_f32 v16, v0, s57, v194
	s_waitcnt lgkmcnt(0)
	v_max_f32_e32 v2, v2, v2
	ds_read2_b32 v[0:1], v5 offset0:12 offset1:77
	v_med3_f32 v17, v2, s57, v194
	v_max_f32_e32 v2, v3, v3
	v_med3_f32 v18, v2, s57, v194
	ds_read2_b32 v[2:3], v5 offset0:142 offset1:207
	s_waitcnt lgkmcnt(1)
	v_max_f32_e32 v0, v0, v0
	v_med3_f32 v19, v0, s57, v194
	v_max_f32_e32 v0, v1, v1
	v_med3_f32 v20, v0, s57, v194
	s_waitcnt lgkmcnt(0)
	v_max_f32_e32 v0, v2, v2
	v_med3_f32 v21, v0, s57, v194
	v_max_f32_e32 v0, v3, v3
	v_med3_f32 v22, v0, s57, v194
	v_add_u32_e32 v0, s22, v6
	v_ashrrev_i32_e32 v1, 31, v0
	v_mul_lo_u32 v2, s10, v1
	v_mul_lo_u32 v3, s11, v0
	v_mad_u64_u32 v[0:1], s[4:5], s10, v0, 0
	v_add3_u32 v1, v1, v2, v3
	v_lshl_add_u64 v[0:1], v[0:1], 1, s[8:9]
	s_ashr_i32 s3, s2, 31
	v_lshl_add_u64 v[0:1], s[2:3], 1, v[0:1]
	v_lshlrev_b32_e32 v112, 1, v4
	v_lshl_add_u64 v[4:5], v[0:1], 0, v[112:113]
	v_cvt_pk_f16_f32 v1, v8, v11
	v_cvt_pk_f16_f32 v0, v7, v10
	v_and_b32_e32 v2, 0xffff0000, v1
	v_lshlrev_b32_e32 v3, 16, v1
	v_or_b32_sdwa v1, v2, v0 dst_sel:DWORD dst_unused:UNUSED_PAD src0_sel:DWORD src1_sel:WORD_1
	v_or_b32_sdwa v0, v3, v0 dst_sel:DWORD dst_unused:UNUSED_PAD src0_sel:DWORD src1_sel:WORD_0
	v_cvt_pk_f16_f32 v3, v12, v15
	v_cvt_pk_f16_f32 v2, v9, v14
	v_and_b32_e32 v6, 0xffff0000, v3
	v_lshlrev_b32_e32 v7, 16, v3
	v_or_b32_sdwa v3, v6, v2 dst_sel:DWORD dst_unused:UNUSED_PAD src0_sel:DWORD src1_sel:WORD_1
	v_or_b32_sdwa v2, v7, v2 dst_sel:DWORD dst_unused:UNUSED_PAD src0_sel:DWORD src1_sel:WORD_0
	global_store_dwordx4 v[4:5], v[0:3], off
	s_add_i32 s0, s0, s59
	s_cmpk_lt_i32 s0, 0x1560
	v_cvt_pk_f16_f32 v1, v16, v18
	v_cvt_pk_f16_f32 v0, v13, v17
	v_and_b32_e32 v2, 0xffff0000, v1
	v_lshlrev_b32_e32 v3, 16, v1
	v_or_b32_sdwa v1, v2, v0 dst_sel:DWORD dst_unused:UNUSED_PAD src0_sel:DWORD src1_sel:WORD_1
	v_or_b32_sdwa v0, v3, v0 dst_sel:DWORD dst_unused:UNUSED_PAD src0_sel:DWORD src1_sel:WORD_0
	v_cvt_pk_f16_f32 v3, v20, v22
	v_cvt_pk_f16_f32 v2, v19, v21
	v_and_b32_e32 v6, 0xffff0000, v3
	v_lshlrev_b32_e32 v7, 16, v3
	v_or_b32_sdwa v3, v6, v2 dst_sel:DWORD dst_unused:UNUSED_PAD src0_sel:DWORD src1_sel:WORD_1
	v_or_b32_sdwa v2, v7, v2 dst_sel:DWORD dst_unused:UNUSED_PAD src0_sel:DWORD src1_sel:WORD_0
	global_store_dwordx4 v[4:5], v[0:3], off offset:16
	s_cbranch_scc0 .LBB0_670

	.amdhsa_kernel _Z14fwd_megakernel6Params
		.amdhsa_group_segment_fixed_size 73732
		.amdhsa_private_segment_fixed_size 0
		.amdhsa_kernarg_size 432
		.amdhsa_user_sgpr_count 2
		.amdhsa_user_sgpr_dispatch_ptr 0
		.amdhsa_user_sgpr_queue_ptr 0
		.amdhsa_user_sgpr_kernarg_segment_ptr 1
		.amdhsa_user_sgpr_dispatch_id 0
		.amdhsa_user_sgpr_kernarg_preload_length 0
		.amdhsa_user_sgpr_kernarg_preload_offset 0
		.amdhsa_user_sgpr_private_segment_size 0
		.amdhsa_uses_dynamic_stack 0
		.amdhsa_enable_private_segment 0
		.amdhsa_system_sgpr_workgroup_id_x 1
		.amdhsa_system_sgpr_workgroup_id_y 0
		.amdhsa_system_sgpr_workgroup_id_z 0
		.amdhsa_system_sgpr_workgroup_info 0
		.amdhsa_system_vgpr_workitem_id 2
		.amdhsa_next_free_vgpr 256
		.amdhsa_next_free_sgpr 102
		.amdhsa_accum_offset 256
		.amdhsa_reserve_vcc 1
		.amdhsa_float_round_mode_32 0
		.amdhsa_float_round_mode_16_64 0
		.amdhsa_float_denorm_mode_32 3
		.amdhsa_float_denorm_mode_16_64 3
		.amdhsa_dx10_clamp 1
		.amdhsa_ieee_mode 1
		.amdhsa_fp16_overflow 0
		.amdhsa_tg_split 0
		.amdhsa_exception_fp_ieee_invalid_op 0
		.amdhsa_exception_fp_denorm_src 0
		.amdhsa_exception_fp_ieee_div_zero 0
		.amdhsa_exception_fp_ieee_overflow 0
		.amdhsa_exception_fp_ieee_underflow 0
		.amdhsa_exception_fp_ieee_inexact 0
		.amdhsa_exception_int_div_zero 0
	.end_amdhsa_kernel

amdhsa.kernels:
  - .agpr_count:     0
    .args:
      - .offset:         0
        .size:           176
        .value_kind:     by_value
      - .offset:         176
        .size:           4
        .value_kind:     hidden_block_count_x
      - .offset:         180
        .size:           4
        .value_kind:     hidden_block_count_y
      - .offset:         184
        .size:           4
        .value_kind:     hidden_block_count_z
      - .offset:         188
        .size:           2
        .value_kind:     hidden_group_size_x
      - .offset:         190
        .size:           2
        .value_kind:     hidden_group_size_y
      - .offset:         192
        .size:           2
        .value_kind:     hidden_group_size_z
      - .offset:         194
        .size:           2
        .value_kind:     hidden_remainder_x
      - .offset:         196
        .size:           2
        .value_kind:     hidden_remainder_y
      - .offset:         198
        .size:           2
        .value_kind:     hidden_remainder_z
      - .offset:         216
        .size:           8
        .value_kind:     hidden_global_offset_x
      - .offset:         224
        .size:           8
        .value_kind:     hidden_global_offset_y
      - .offset:         232
        .size:           8
        .value_kind:     hidden_global_offset_z
      - .offset:         240
        .size:           2
        .value_kind:     hidden_grid_dims
      - .offset:         264
        .size:           8
        .value_kind:     hidden_multigrid_sync_arg
    .group_segment_fixed_size: 73732
    .kernarg_segment_align: 8
    .kernarg_segment_size: 432
    .language:       OpenCL C
    .language_version:
      - 2
      - 0
    .max_flat_workgroup_size: 256
    .name:           _Z14fwd_megakernel6Params
    .private_segment_fixed_size: 0
    .sgpr_count:     108
    .sgpr_spill_count: 175
    .symbol:         _Z14fwd_megakernel6Params.kd
    .uniform_work_group_size: 1
    .uses_dynamic_stack: false
    .vgpr_count:     256
    .vgpr_spill_count: 0
    .wavefront_size: 64
